# W pass and H3 pass: operands loaded three tokens ahead (four rotating buffers)
# baseline (speedup 1.0000x reference)
; __device__ __forceinline__ float gelu_tanh(float x) {
;   float u = 0.7978845608028654f * (x + 0.044715f * x * x * x);
;   return 0.5f * x * (1.f + tanhf(u));
; }
.Lp5w_start:
	v_mbcnt_lo_u32_b32 v0, -1, 0
	v_mbcnt_hi_u32_b32 v0, -1, v0
	v_accvgpr_read_b32 v4, a129
	v_lshlrev_b32_e32 v1, 3, v0
	v_readfirstlane_b32 s8, v4
	s_lshl_b32 s10, s96, 2
	s_add_u32 s8, s8, s10
	s_lshl_b32 s9, s82, 2
	s_add_u32 s4, s80, 0x3bb5000
	s_addc_u32 s5, s81, 0
	s_add_u32 s6, s80, 0xcf35000
	s_addc_u32 s7, s81, 0
	s_mov_b32 s33, 0x3fb8aa3b
	s_mov_b32 s34, 0xc2ce8ed0
	s_mov_b32 s35, 0x42b17218
	s_mov_b32 s36, 0x3f200000
	s_brev_b32 s37, -2
	v_mov_b32_e32 v2, 0x7f800000
	v_mov_b32_e32 v3, 0x3ca908c9
	s_movk_i32 s13, 0x41ff
	s_mul_i32 s20, s9, 1
	s_mul_i32 s21, s9, 2
	s_mul_i32 s22, s9, 3
	s_mul_i32 s23, s9, 4
	s_mul_i32 s24, s9, 5
	s_mul_i32 s25, s9, 6
	s_mul_i32 s26, s9, 7
	s_min_u32 s12, s8, s13
	s_lshl_b32 s11, s12, 12
	v_add_u32_e32 v5, s11, v1
	global_load_dwordx2 v[64:65], v5, s[6:7] offset:0
	global_load_dwordx2 v[66:67], v5, s[6:7] offset:512
	global_load_dwordx2 v[68:69], v5, s[6:7] offset:1024
	global_load_dwordx2 v[70:71], v5, s[6:7] offset:1536
	global_load_dwordx2 v[72:73], v5, s[6:7] offset:2048
	global_load_dwordx2 v[74:75], v5, s[6:7] offset:2560
	global_load_dwordx2 v[76:77], v5, s[6:7] offset:3072
	global_load_dwordx2 v[78:79], v5, s[6:7] offset:3584
	s_lshl_b32 s11, s12, 10
	v_add_u32_e32 v6, s11, v1
	global_load_dwordx2 v[80:81], v6, s[4:5] offset:512
	global_load_dword v252, v6, s[4:5]
	s_add_u32 s12, s8, s20
	s_min_u32 s12, s12, s13
	s_lshl_b32 s11, s12, 12
	v_add_u32_e32 v5, s11, v1
	global_load_dwordx2 v[88:89], v5, s[6:7] offset:0
	global_load_dwordx2 v[90:91], v5, s[6:7] offset:512
	global_load_dwordx2 v[92:93], v5, s[6:7] offset:1024
	global_load_dwordx2 v[94:95], v5, s[6:7] offset:1536
	global_load_dwordx2 v[96:97], v5, s[6:7] offset:2048
	global_load_dwordx2 v[98:99], v5, s[6:7] offset:2560
	global_load_dwordx2 v[100:101], v5, s[6:7] offset:3072
	global_load_dwordx2 v[102:103], v5, s[6:7] offset:3584
	s_lshl_b32 s11, s12, 10
	v_add_u32_e32 v6, s11, v1
	global_load_dwordx2 v[104:105], v6, s[4:5] offset:512
	global_load_dword v252, v6, s[4:5]
	s_add_u32 s12, s8, s21
	s_min_u32 s12, s12, s13
	s_lshl_b32 s11, s12, 12
	v_add_u32_e32 v5, s11, v1
	global_load_dwordx2 v[112:113], v5, s[6:7] offset:0
	global_load_dwordx2 v[114:115], v5, s[6:7] offset:512
	global_load_dwordx2 v[116:117], v5, s[6:7] offset:1024
	global_load_dwordx2 v[118:119], v5, s[6:7] offset:1536
	global_load_dwordx2 v[120:121], v5, s[6:7] offset:2048
	global_load_dwordx2 v[122:123], v5, s[6:7] offset:2560
	global_load_dwordx2 v[124:125], v5, s[6:7] offset:3072
	global_load_dwordx2 v[126:127], v5, s[6:7] offset:3584
	s_lshl_b32 s11, s12, 10
	v_add_u32_e32 v6, s11, v1
	global_load_dwordx2 v[128:129], v6, s[4:5] offset:512
	global_load_dword v252, v6, s[4:5]
.Lp5w_loop:
	s_add_u32 s12, s8, s22
	s_min_u32 s12, s12, s13
	s_lshl_b32 s11, s12, 12
	v_add_u32_e32 v5, s11, v1
	global_load_dwordx2 v[136:137], v5, s[6:7] offset:0
	global_load_dwordx2 v[138:139], v5, s[6:7] offset:512
	global_load_dwordx2 v[140:141], v5, s[6:7] offset:1024
	global_load_dwordx2 v[142:143], v5, s[6:7] offset:1536
	global_load_dwordx2 v[144:145], v5, s[6:7] offset:2048
	global_load_dwordx2 v[146:147], v5, s[6:7] offset:2560
	global_load_dwordx2 v[148:149], v5, s[6:7] offset:3072
	global_load_dwordx2 v[150:151], v5, s[6:7] offset:3584
	s_lshl_b32 s11, s12, 10
	v_add_u32_e32 v6, s11, v1
	global_load_dwordx2 v[152:153], v6, s[4:5] offset:512
	s_waitcnt vmcnt(30)
	s_mov_b32 s14, s8
	s_cmp_lt_u32 s14, 0x4200
	s_cbranch_scc0 .Lp5w_done
	v_pk_add_f32 v[64:65], v[64:65], v[66:67]
	v_pk_add_f32 v[64:65], v[64:65], v[68:69]
	v_pk_add_f32 v[64:65], v[64:65], v[70:71]
	v_pk_add_f32 v[64:65], v[64:65], v[72:73]
	v_pk_add_f32 v[64:65], v[64:65], v[74:75]
	v_pk_add_f32 v[64:65], v[64:65], v[76:77]
	v_pk_add_f32 v[64:65], v[64:65], v[78:79]
	v_mul_f32_e32 v64, 0x3c800000, v64
	v_mul_f32_e32 v10, 0x3d372713, v64
	v_mul_f32_e32 v10, v64, v10
	v_fma_f32 v10, v64, v10, v64
	v_mul_f32_e32 v11, 0x3f4c422a, v10
	v_add_f32_e64 v12, |v11|, |v11|
	v_mul_f32_e32 v13, 0x3fb8aa3b, v12
	v_rndne_f32_e32 v14, v13
	v_sub_f32_e32 v15, v13, v14
	v_fma_f32 v13, v12, s33, -v13
	v_fmac_f32_e32 v13, 0x32a5705f, v12
	v_add_f32_e32 v13, v15, v13
	v_cvt_i32_f32_e32 v14, v14
	v_exp_f32_e32 v13, v13
	v_cmp_ngt_f32_e32 vcc, s34, v12
	v_ldexp_f32 v13, v13, v14
	s_nop 0
	v_cndmask_b32_e32 v13, 0, v13, vcc
	v_cmp_nlt_f32_e32 vcc, s35, v12
	s_nop 1
	v_cndmask_b32_e32 v12, v2, v13, vcc
	v_add_f32_e32 v12, 1.0, v12
	v_rcp_f32_e32 v12, v12
	s_nop 0
	v_fma_f32 v16, v12, -2.0, 1.0
	v_mul_f32_e32 v12, v11, v11
	v_fmamk_f32 v13, v12, 0xbbbac73d, v3
	v_fmaak_f32 v13, v12, v13, 0xbd5c1c4e
	v_fmaak_f32 v13, v12, v13, 0x3e088382
	v_fmaak_f32 v13, v12, v13, 0xbeaaaa99
	v_mul_f32_e64 v13, |v11|, v13
	v_fma_f32 v17, v12, v13, |v11|
	v_cmp_nlt_f32_e64 vcc, |v11|, s36
	s_nop 1
	v_cndmask_b32_e32 v16, v17, v16, vcc
	v_bfi_b32 v16, s37, v16, v11
	v_mul_f32_e32 v10, 0.5, v64
	v_add_f32_e32 v16, 1.0, v16
	v_mul_f32_e32 v10, v10, v16
	v_mul_f32_e32 v10, v80, v10
	v_mul_f32_e32 v20, 0x3d800000, v10
	v_mul_f32_e32 v65, 0x3c800000, v65
	v_mul_f32_e32 v10, 0x3d372713, v65
	v_mul_f32_e32 v10, v65, v10
	v_fma_f32 v10, v65, v10, v65
	v_mul_f32_e32 v11, 0x3f4c422a, v10
	v_add_f32_e64 v12, |v11|, |v11|
	v_mul_f32_e32 v13, 0x3fb8aa3b, v12
	v_rndne_f32_e32 v14, v13
	v_sub_f32_e32 v15, v13, v14
	v_fma_f32 v13, v12, s33, -v13
	v_fmac_f32_e32 v13, 0x32a5705f, v12
	v_add_f32_e32 v13, v15, v13
	v_cvt_i32_f32_e32 v14, v14
	v_exp_f32_e32 v13, v13
	v_cmp_ngt_f32_e32 vcc, s34, v12
	v_ldexp_f32 v13, v13, v14
	s_nop 0
	v_cndmask_b32_e32 v13, 0, v13, vcc
	v_cmp_nlt_f32_e32 vcc, s35, v12
	s_nop 1
	v_cndmask_b32_e32 v12, v2, v13, vcc
	v_add_f32_e32 v12, 1.0, v12
	v_rcp_f32_e32 v12, v12
	s_nop 0
	v_fma_f32 v16, v12, -2.0, 1.0
	v_mul_f32_e32 v12, v11, v11
	v_fmamk_f32 v13, v12, 0xbbbac73d, v3
	v_fmaak_f32 v13, v12, v13, 0xbd5c1c4e
	v_fmaak_f32 v13, v12, v13, 0x3e088382
	v_fmaak_f32 v13, v12, v13, 0xbeaaaa99
	v_mul_f32_e64 v13, |v11|, v13
	v_fma_f32 v17, v12, v13, |v11|
	v_cmp_nlt_f32_e64 vcc, |v11|, s36
	s_nop 1
	v_cndmask_b32_e32 v16, v17, v16, vcc
	v_bfi_b32 v16, s37, v16, v11
	v_mul_f32_e32 v10, 0.5, v65
	v_add_f32_e32 v16, 1.0, v16
	v_mul_f32_e32 v10, v10, v16
	v_mul_f32_e32 v10, v81, v10
	v_mul_f32_e32 v21, 0x3d800000, v10
	s_lshl_b32 s11, s14, 10
	v_add_u32_e32 v6, s11, v1
	global_store_dwordx2 v6, v[20:21], s[4:5] offset:512
	s_add_u32 s12, s8, s23
	s_min_u32 s12, s12, s13
	s_lshl_b32 s11, s12, 12
	v_add_u32_e32 v5, s11, v1
	global_load_dwordx2 v[64:65], v5, s[6:7] offset:0
	global_load_dwordx2 v[66:67], v5, s[6:7] offset:512
	global_load_dwordx2 v[68:69], v5, s[6:7] offset:1024
	global_load_dwordx2 v[70:71], v5, s[6:7] offset:1536
	global_load_dwordx2 v[72:73], v5, s[6:7] offset:2048
	global_load_dwordx2 v[74:75], v5, s[6:7] offset:2560
	global_load_dwordx2 v[76:77], v5, s[6:7] offset:3072
	global_load_dwordx2 v[78:79], v5, s[6:7] offset:3584
	s_lshl_b32 s11, s12, 10
	v_add_u32_e32 v6, s11, v1
	global_load_dwordx2 v[80:81], v6, s[4:5] offset:512
	s_waitcnt vmcnt(30)
; __device__ __forceinline__ float gelu_tanh(float x) {
;   float u = 0.7978845608028654f * (x + 0.044715f * x * x * x);
;   return 0.5f * x * (1.f + tanhf(u));
; }
	s_add_u32 s14, s8, s20
	s_cmp_lt_u32 s14, 0x4200
	s_cbranch_scc0 .Lp5w_done
	v_pk_add_f32 v[88:89], v[88:89], v[90:91]
	v_pk_add_f32 v[88:89], v[88:89], v[92:93]
	v_pk_add_f32 v[88:89], v[88:89], v[94:95]
	v_pk_add_f32 v[88:89], v[88:89], v[96:97]
	v_pk_add_f32 v[88:89], v[88:89], v[98:99]
	v_pk_add_f32 v[88:89], v[88:89], v[100:101]
	v_pk_add_f32 v[88:89], v[88:89], v[102:103]
	v_mul_f32_e32 v88, 0x3c800000, v88
	v_mul_f32_e32 v10, 0x3d372713, v88
	v_mul_f32_e32 v10, v88, v10
	v_fma_f32 v10, v88, v10, v88
	v_mul_f32_e32 v11, 0x3f4c422a, v10
	v_add_f32_e64 v12, |v11|, |v11|
	v_mul_f32_e32 v13, 0x3fb8aa3b, v12
	v_rndne_f32_e32 v14, v13
	v_sub_f32_e32 v15, v13, v14
	v_fma_f32 v13, v12, s33, -v13
	v_fmac_f32_e32 v13, 0x32a5705f, v12
	v_add_f32_e32 v13, v15, v13
	v_cvt_i32_f32_e32 v14, v14
	v_exp_f32_e32 v13, v13
	v_cmp_ngt_f32_e32 vcc, s34, v12
	v_ldexp_f32 v13, v13, v14
	s_nop 0
	v_cndmask_b32_e32 v13, 0, v13, vcc
	v_cmp_nlt_f32_e32 vcc, s35, v12
	s_nop 1
	v_cndmask_b32_e32 v12, v2, v13, vcc
	v_add_f32_e32 v12, 1.0, v12
	v_rcp_f32_e32 v12, v12
	s_nop 0
	v_fma_f32 v16, v12, -2.0, 1.0
	v_mul_f32_e32 v12, v11, v11
	v_fmamk_f32 v13, v12, 0xbbbac73d, v3
	v_fmaak_f32 v13, v12, v13, 0xbd5c1c4e
	v_fmaak_f32 v13, v12, v13, 0x3e088382
	v_fmaak_f32 v13, v12, v13, 0xbeaaaa99
	v_mul_f32_e64 v13, |v11|, v13
	v_fma_f32 v17, v12, v13, |v11|
	v_cmp_nlt_f32_e64 vcc, |v11|, s36
	s_nop 1
	v_cndmask_b32_e32 v16, v17, v16, vcc
	v_bfi_b32 v16, s37, v16, v11
	v_mul_f32_e32 v10, 0.5, v88
	v_add_f32_e32 v16, 1.0, v16
	v_mul_f32_e32 v10, v10, v16
	v_mul_f32_e32 v10, v104, v10
	v_mul_f32_e32 v20, 0x3d800000, v10
	v_mul_f32_e32 v89, 0x3c800000, v89
	v_mul_f32_e32 v10, 0x3d372713, v89
	v_mul_f32_e32 v10, v89, v10
	v_fma_f32 v10, v89, v10, v89
	v_mul_f32_e32 v11, 0x3f4c422a, v10
	v_add_f32_e64 v12, |v11|, |v11|
	v_mul_f32_e32 v13, 0x3fb8aa3b, v12
	v_rndne_f32_e32 v14, v13
	v_sub_f32_e32 v15, v13, v14
	v_fma_f32 v13, v12, s33, -v13
	v_fmac_f32_e32 v13, 0x32a5705f, v12
	v_add_f32_e32 v13, v15, v13
	v_cvt_i32_f32_e32 v14, v14
	v_exp_f32_e32 v13, v13
	v_cmp_ngt_f32_e32 vcc, s34, v12
	v_ldexp_f32 v13, v13, v14
	s_nop 0
	v_cndmask_b32_e32 v13, 0, v13, vcc
	v_cmp_nlt_f32_e32 vcc, s35, v12
	s_nop 1
	v_cndmask_b32_e32 v12, v2, v13, vcc
	v_add_f32_e32 v12, 1.0, v12
	v_rcp_f32_e32 v12, v12
	s_nop 0
	v_fma_f32 v16, v12, -2.0, 1.0
	v_mul_f32_e32 v12, v11, v11
	v_fmamk_f32 v13, v12, 0xbbbac73d, v3
	v_fmaak_f32 v13, v12, v13, 0xbd5c1c4e
	v_fmaak_f32 v13, v12, v13, 0x3e088382
	v_fmaak_f32 v13, v12, v13, 0xbeaaaa99
	v_mul_f32_e64 v13, |v11|, v13
	v_fma_f32 v17, v12, v13, |v11|
	v_cmp_nlt_f32_e64 vcc, |v11|, s36
	s_nop 1
	v_cndmask_b32_e32 v16, v17, v16, vcc
	v_bfi_b32 v16, s37, v16, v11
	v_mul_f32_e32 v10, 0.5, v89
	v_add_f32_e32 v16, 1.0, v16
	v_mul_f32_e32 v10, v10, v16
	v_mul_f32_e32 v10, v105, v10
	v_mul_f32_e32 v21, 0x3d800000, v10
	s_lshl_b32 s11, s14, 10
	v_add_u32_e32 v6, s11, v1
	global_store_dwordx2 v6, v[20:21], s[4:5] offset:512
	s_add_u32 s12, s8, s24
	s_min_u32 s12, s12, s13
	s_lshl_b32 s11, s12, 12
	v_add_u32_e32 v5, s11, v1
	global_load_dwordx2 v[88:89], v5, s[6:7] offset:0
	global_load_dwordx2 v[90:91], v5, s[6:7] offset:512
	global_load_dwordx2 v[92:93], v5, s[6:7] offset:1024
	global_load_dwordx2 v[94:95], v5, s[6:7] offset:1536
	global_load_dwordx2 v[96:97], v5, s[6:7] offset:2048
	global_load_dwordx2 v[98:99], v5, s[6:7] offset:2560
	global_load_dwordx2 v[100:101], v5, s[6:7] offset:3072
	global_load_dwordx2 v[102:103], v5, s[6:7] offset:3584
	s_lshl_b32 s11, s12, 10
	v_add_u32_e32 v6, s11, v1
	global_load_dwordx2 v[104:105], v6, s[4:5] offset:512
	s_waitcnt vmcnt(30)
	s_add_u32 s14, s8, s21
	s_cmp_lt_u32 s14, 0x4200
	s_cbranch_scc0 .Lp5w_done
; __device__ __forceinline__ float gelu_tanh(float x) {
;   float u = 0.7978845608028654f * (x + 0.044715f * x * x * x);
;   return 0.5f * x * (1.f + tanhf(u));
; }
	v_pk_add_f32 v[112:113], v[112:113], v[114:115]
	v_pk_add_f32 v[112:113], v[112:113], v[116:117]
	v_pk_add_f32 v[112:113], v[112:113], v[118:119]
	v_pk_add_f32 v[112:113], v[112:113], v[120:121]
	v_pk_add_f32 v[112:113], v[112:113], v[122:123]
	v_pk_add_f32 v[112:113], v[112:113], v[124:125]
	v_pk_add_f32 v[112:113], v[112:113], v[126:127]
	v_mul_f32_e32 v112, 0x3c800000, v112
	v_mul_f32_e32 v10, 0x3d372713, v112
	v_mul_f32_e32 v10, v112, v10
	v_fma_f32 v10, v112, v10, v112
	v_mul_f32_e32 v11, 0x3f4c422a, v10
	v_add_f32_e64 v12, |v11|, |v11|
	v_mul_f32_e32 v13, 0x3fb8aa3b, v12
	v_rndne_f32_e32 v14, v13
	v_sub_f32_e32 v15, v13, v14
	v_fma_f32 v13, v12, s33, -v13
	v_fmac_f32_e32 v13, 0x32a5705f, v12
	v_add_f32_e32 v13, v15, v13
	v_cvt_i32_f32_e32 v14, v14
	v_exp_f32_e32 v13, v13
	v_cmp_ngt_f32_e32 vcc, s34, v12
	v_ldexp_f32 v13, v13, v14
	s_nop 0
	v_cndmask_b32_e32 v13, 0, v13, vcc
	v_cmp_nlt_f32_e32 vcc, s35, v12
	s_nop 1
	v_cndmask_b32_e32 v12, v2, v13, vcc
	v_add_f32_e32 v12, 1.0, v12
	v_rcp_f32_e32 v12, v12
	s_nop 0
	v_fma_f32 v16, v12, -2.0, 1.0
	v_mul_f32_e32 v12, v11, v11
	v_fmamk_f32 v13, v12, 0xbbbac73d, v3
	v_fmaak_f32 v13, v12, v13, 0xbd5c1c4e
	v_fmaak_f32 v13, v12, v13, 0x3e088382
	v_fmaak_f32 v13, v12, v13, 0xbeaaaa99
	v_mul_f32_e64 v13, |v11|, v13
	v_fma_f32 v17, v12, v13, |v11|
	v_cmp_nlt_f32_e64 vcc, |v11|, s36
	s_nop 1
	v_cndmask_b32_e32 v16, v17, v16, vcc
	v_bfi_b32 v16, s37, v16, v11
	v_mul_f32_e32 v10, 0.5, v112
	v_add_f32_e32 v16, 1.0, v16
	v_mul_f32_e32 v10, v10, v16
	v_mul_f32_e32 v10, v128, v10
	v_mul_f32_e32 v20, 0x3d800000, v10
	v_mul_f32_e32 v113, 0x3c800000, v113
	v_mul_f32_e32 v10, 0x3d372713, v113
	v_mul_f32_e32 v10, v113, v10
	v_fma_f32 v10, v113, v10, v113
	v_mul_f32_e32 v11, 0x3f4c422a, v10
	v_add_f32_e64 v12, |v11|, |v11|
	v_mul_f32_e32 v13, 0x3fb8aa3b, v12
	v_rndne_f32_e32 v14, v13
	v_sub_f32_e32 v15, v13, v14
	v_fma_f32 v13, v12, s33, -v13
	v_fmac_f32_e32 v13, 0x32a5705f, v12
	v_add_f32_e32 v13, v15, v13
	v_cvt_i32_f32_e32 v14, v14
	v_exp_f32_e32 v13, v13
	v_cmp_ngt_f32_e32 vcc, s34, v12
	v_ldexp_f32 v13, v13, v14
	s_nop 0
	v_cndmask_b32_e32 v13, 0, v13, vcc
	v_cmp_nlt_f32_e32 vcc, s35, v12
	s_nop 1
	v_cndmask_b32_e32 v12, v2, v13, vcc
	v_add_f32_e32 v12, 1.0, v12
	v_rcp_f32_e32 v12, v12
	s_nop 0
	v_fma_f32 v16, v12, -2.0, 1.0
	v_mul_f32_e32 v12, v11, v11
	v_fmamk_f32 v13, v12, 0xbbbac73d, v3
	v_fmaak_f32 v13, v12, v13, 0xbd5c1c4e
	v_fmaak_f32 v13, v12, v13, 0x3e088382
	v_fmaak_f32 v13, v12, v13, 0xbeaaaa99
	v_mul_f32_e64 v13, |v11|, v13
	v_fma_f32 v17, v12, v13, |v11|
	v_cmp_nlt_f32_e64 vcc, |v11|, s36
	s_nop 1
	v_cndmask_b32_e32 v16, v17, v16, vcc
	v_bfi_b32 v16, s37, v16, v11
	v_mul_f32_e32 v10, 0.5, v113
	v_add_f32_e32 v16, 1.0, v16
	v_mul_f32_e32 v10, v10, v16
	v_mul_f32_e32 v10, v129, v10
	v_mul_f32_e32 v21, 0x3d800000, v10
	s_lshl_b32 s11, s14, 10
	v_add_u32_e32 v6, s11, v1
	global_store_dwordx2 v6, v[20:21], s[4:5] offset:512
	s_add_u32 s12, s8, s25
	s_min_u32 s12, s12, s13
	s_lshl_b32 s11, s12, 12
	v_add_u32_e32 v5, s11, v1
	global_load_dwordx2 v[112:113], v5, s[6:7] offset:0
	global_load_dwordx2 v[114:115], v5, s[6:7] offset:512
	global_load_dwordx2 v[116:117], v5, s[6:7] offset:1024
	global_load_dwordx2 v[118:119], v5, s[6:7] offset:1536
	global_load_dwordx2 v[120:121], v5, s[6:7] offset:2048
	global_load_dwordx2 v[122:123], v5, s[6:7] offset:2560
	global_load_dwordx2 v[124:125], v5, s[6:7] offset:3072
	global_load_dwordx2 v[126:127], v5, s[6:7] offset:3584
	s_lshl_b32 s11, s12, 10
	v_add_u32_e32 v6, s11, v1
	global_load_dwordx2 v[128:129], v6, s[4:5] offset:512
	s_waitcnt vmcnt(30)
	s_add_u32 s14, s8, s22
	s_cmp_lt_u32 s14, 0x4200
	s_cbranch_scc0 .Lp5w_done
	v_pk_add_f32 v[136:137], v[136:137], v[138:139]
	v_pk_add_f32 v[136:137], v[136:137], v[140:141]
	v_pk_add_f32 v[136:137], v[136:137], v[142:143]
	v_pk_add_f32 v[136:137], v[136:137], v[144:145]
	v_pk_add_f32 v[136:137], v[136:137], v[146:147]
	v_pk_add_f32 v[136:137], v[136:137], v[148:149]
	v_pk_add_f32 v[136:137], v[136:137], v[150:151]
	v_mul_f32_e32 v136, 0x3c800000, v136
	v_mul_f32_e32 v10, 0x3d372713, v136
	v_mul_f32_e32 v10, v136, v10
	v_fma_f32 v10, v136, v10, v136
	v_mul_f32_e32 v11, 0x3f4c422a, v10
	v_add_f32_e64 v12, |v11|, |v11|
	v_mul_f32_e32 v13, 0x3fb8aa3b, v12
	v_rndne_f32_e32 v14, v13
	v_sub_f32_e32 v15, v13, v14
	v_fma_f32 v13, v12, s33, -v13
	v_fmac_f32_e32 v13, 0x32a5705f, v12
	v_add_f32_e32 v13, v15, v13
	v_cvt_i32_f32_e32 v14, v14
	v_exp_f32_e32 v13, v13
	v_cmp_ngt_f32_e32 vcc, s34, v12
	v_ldexp_f32 v13, v13, v14
	s_nop 0
	v_cndmask_b32_e32 v13, 0, v13, vcc
	v_cmp_nlt_f32_e32 vcc, s35, v12
	s_nop 1
	v_cndmask_b32_e32 v12, v2, v13, vcc
	v_add_f32_e32 v12, 1.0, v12
	v_rcp_f32_e32 v12, v12
	s_nop 0
	v_fma_f32 v16, v12, -2.0, 1.0
	v_mul_f32_e32 v12, v11, v11
	v_fmamk_f32 v13, v12, 0xbbbac73d, v3
	v_fmaak_f32 v13, v12, v13, 0xbd5c1c4e
	v_fmaak_f32 v13, v12, v13, 0x3e088382
	v_fmaak_f32 v13, v12, v13, 0xbeaaaa99
	v_mul_f32_e64 v13, |v11|, v13
	v_fma_f32 v17, v12, v13, |v11|
	v_cmp_nlt_f32_e64 vcc, |v11|, s36
	s_nop 1
	v_cndmask_b32_e32 v16, v17, v16, vcc
	v_bfi_b32 v16, s37, v16, v11
	v_mul_f32_e32 v10, 0.5, v136
	v_add_f32_e32 v16, 1.0, v16
	v_mul_f32_e32 v10, v10, v16
	v_mul_f32_e32 v10, v152, v10
	v_mul_f32_e32 v20, 0x3d800000, v10
	v_mul_f32_e32 v137, 0x3c800000, v137
	v_mul_f32_e32 v10, 0x3d372713, v137
	v_mul_f32_e32 v10, v137, v10
	v_fma_f32 v10, v137, v10, v137
	v_mul_f32_e32 v11, 0x3f4c422a, v10
	v_add_f32_e64 v12, |v11|, |v11|
	v_mul_f32_e32 v13, 0x3fb8aa3b, v12
	v_rndne_f32_e32 v14, v13
	v_sub_f32_e32 v15, v13, v14
	v_fma_f32 v13, v12, s33, -v13
	v_fmac_f32_e32 v13, 0x32a5705f, v12
	v_add_f32_e32 v13, v15, v13
	v_cvt_i32_f32_e32 v14, v14
	v_exp_f32_e32 v13, v13
	v_cmp_ngt_f32_e32 vcc, s34, v12
	v_ldexp_f32 v13, v13, v14
	s_nop 0
	v_cndmask_b32_e32 v13, 0, v13, vcc
	v_cmp_nlt_f32_e32 vcc, s35, v12
	s_nop 1
	v_cndmask_b32_e32 v12, v2, v13, vcc
	v_add_f32_e32 v12, 1.0, v12
	v_rcp_f32_e32 v12, v12
	s_nop 0
	v_fma_f32 v16, v12, -2.0, 1.0
	v_mul_f32_e32 v12, v11, v11
	v_fmamk_f32 v13, v12, 0xbbbac73d, v3
	v_fmaak_f32 v13, v12, v13, 0xbd5c1c4e
	v_fmaak_f32 v13, v12, v13, 0x3e088382
	v_fmaak_f32 v13, v12, v13, 0xbeaaaa99
	v_mul_f32_e64 v13, |v11|, v13
	v_fma_f32 v17, v12, v13, |v11|
	v_cmp_nlt_f32_e64 vcc, |v11|, s36
	s_nop 1
	v_cndmask_b32_e32 v16, v17, v16, vcc
	v_bfi_b32 v16, s37, v16, v11
	v_mul_f32_e32 v10, 0.5, v137
	v_add_f32_e32 v16, 1.0, v16
	v_mul_f32_e32 v10, v10, v16
	v_mul_f32_e32 v10, v153, v10
	v_mul_f32_e32 v21, 0x3d800000, v10
	s_lshl_b32 s11, s14, 10
	v_add_u32_e32 v6, s11, v1
	global_store_dwordx2 v6, v[20:21], s[4:5] offset:512
	s_add_u32 s8, s8, s23
	s_branch .Lp5w_loop
.Lp5w_done:
	s_waitcnt vmcnt(0)
.Lpb3_1523:
	s_waitcnt vmcnt(0)
	s_barrier
	s_and_saveexec_b64 s[0:1], s[72:73]
	s_cbranch_execz .Lpb3_1575

; __device__ __forceinline__ void xcd_barrier(const XcdBarrier& b) {
;     asm volatile("s_waitcnt vmcnt(0)" ::: "memory");
;     __syncthreads();
;     if (threadIdx.x == 0) {
;         unsigned* bar = b.bar;
;         __builtin_amdgcn_s_waitcnt(0);
;         unsigned nloc = b.st[0], nx = b.st[1];
;         if (nloc == 0u) { xcd_barrier_complete(bar, b.x, nloc, nx); b.st[0] = nloc; b.st[1] = nx; }
	v_mov_b32_e32 v0, 0x23800
	s_waitcnt vmcnt(0) expcnt(0) lgkmcnt(0)
	ds_read_b32 v2, v0
	v_mov_b32_e32 v0, 0x23804
	ds_read_b32 v0, v0
	s_waitcnt lgkmcnt(1)
	v_cmp_ne_u32_e32 vcc, 0, v2
	s_cbranch_vccnz .Lpb3_1539

; __device__ __forceinline__ unsigned xb_ld(unsigned* p)              { return __hip_atomic_load(p, __ATOMIC_RELAXED, __HIP_MEMORY_SCOPE_AGENT); }
; __device__ __forceinline__ void xcd_barrier_complete(unsigned* bar, unsigned x, unsigned& nloc, unsigned& nx) {
;     const unsigned G = gridDim.x * gridDim.y * gridDim.z;
;     unsigned sum, cnt, mine, sp = 0u;
;     for (;;) {
;         sum = 0u; cnt = 0u; mine = 0u;
; #pragma unroll
;         for (unsigned j = 0; j < 16; ++j) { const unsigned c = xb_ld(&bar[XB_XCNT(j)]); sum += c; cnt += (c > 0u) ? 1u : 0u; mine = (j == x) ? c : mine; }
	v_readlane_b32 s4, v254, 0
	s_mul_i32 s33, s83, s4
	s_add_u32 s4, s80, 0x12f35200
	s_addc_u32 s5, s81, 0
	s_add_u32 s6, s80, 0x12f35400
	s_addc_u32 s7, s81, 0
	s_add_u32 s8, s80, 0x12f35500
	s_addc_u32 s9, s81, 0
	s_add_u32 s10, s80, 0x12f35600
	s_addc_u32 s11, s81, 0
	s_add_u32 s12, s80, 0x12f35700
	s_addc_u32 s13, s81, 0
	s_add_u32 s14, s80, 0x12f35800
	s_addc_u32 s15, s81, 0
	s_add_u32 s16, s80, 0x12f35900
	s_addc_u32 s17, s81, 0
	s_add_u32 s18, s80, 0x12f35a00
	s_addc_u32 s19, s81, 0
	s_add_u32 s20, s80, 0x12f35b00
	s_addc_u32 s21, s81, 0
	s_add_u32 s22, s80, 0x12f35c00
	s_addc_u32 s23, s81, 0
	s_add_u32 s24, s80, 0x12f35d00
	s_addc_u32 s25, s81, 0
	s_add_u32 s26, s80, 0x12f35e00
	s_addc_u32 s27, s81, 0
	s_add_u32 s28, s80, 0x12f35f00
	s_addc_u32 s29, s81, 0
	s_add_u32 s34, s80, 0x12f36000
	s_addc_u32 s35, s81, 0
	s_add_u32 s36, s80, 0x12f36100
	s_addc_u32 s37, s81, 0
	s_add_u32 s38, s80, 0x12f36200
	s_addc_u32 s39, s81, 0
	s_add_u32 s40, s80, 0x12f36300
	s_mul_i32 s33, s33, s82
	s_addc_u32 s41, s81, 0
	s_mov_b32 s48, 1
	v_mov_b32_e32 v16, 0
	s_branch .Lpb3_1527

; __device__ __forceinline__ float bflo(unsigned u) { return __uint_as_float(u << 16); }
; __device__ __forceinline__ float bfhi(unsigned u) { return __uint_as_float(u & 0xffff0000u); }
; __device__ __forceinline__ void phase5(const Params& p, char* smem, const bool store_x = true) {
;     ...
;     const uint4 cur_ha = pf_ha, cur_hb = pf_hb; const float cur_rs = rsqrtf(pf_ss * (1.f / 1024.f) + EPSF);
;     ...
;     float2v h2[8];
;     {
;       const uint4 a = cur_ha;
;       const uint4 b2 = cur_hb;
;       h2[0] = float2v{bflo(a.x), bfhi(a.x)}; h2[1] = float2v{bflo(a.y), bfhi(a.y)}; h2[2] = float2v{bflo(a.z), bfhi(a.z)}; h2[3] = float2v{bflo(a.w), bfhi(a.w)};
;       h2[4] = float2v{bflo(b2.x), bfhi(b2.x)}; h2[5] = float2v{bflo(b2.y), bfhi(b2.y)}; h2[6] = float2v{bflo(b2.z), bfhi(b2.z)}; h2[7] = float2v{bflo(b2.w), bfhi(b2.w)};
; #pragma unroll
;       for (int i = 0; i < 8; i++) h2[i] = h2[i] * gf[i] * cur_rs;
;     }
.Lp5h_start:
	v_mbcnt_lo_u32_b32 v0, -1, 0
	v_mbcnt_hi_u32_b32 v0, -1, v0
	v_accvgpr_read_b32 v4, a129
	v_readlane_b32 s70, v254, 33
	v_readlane_b32 s71, v254, 34
	v_lshlrev_b32_e32 v1, 6, v0
	v_lshlrev_b32_e32 v2, 5, v0
	v_readfirstlane_b32 s8, v4
	s_lshl_b32 s10, s96, 2
	s_add_u32 s8, s8, s10
	s_lshl_b32 s9, s82, 2
	s_add_u32 s4, s80, 0x3bb5000
	s_addc_u32 s5, s81, 0
	s_add_u32 s2, s80, 0x8e35000
	s_addc_u32 s3, s81, 0
	global_load_dwordx4 v[112:115], v1, s[70:71]
	global_load_dwordx4 v[116:119], v1, s[70:71] offset:16
	global_load_dwordx4 v[120:123], v1, s[70:71] offset:32
	global_load_dwordx4 v[124:127], v1, s[70:71] offset:48
	v_mov_b32_e32 v105, 0x358637bd
	s_mov_b32 s39, 0x800000
	s_movk_i32 s13, 0x41ff
	s_mul_i32 s20, s9, 1
	s_mul_i32 s21, s9, 2
	s_mul_i32 s22, s9, 3
	s_mul_i32 s23, s9, 4
	s_mul_i32 s24, s9, 5
	s_mul_i32 s25, s9, 6
	s_mul_i32 s26, s9, 7
	s_min_u32 s12, s8, s13
	s_lshl_b32 s11, s12, 12
	v_add_u32_e32 v5, s11, v1
	global_load_dwordx4 v[64:67], v5, s[78:79] offset:0
	global_load_dwordx4 v[68:71], v5, s[78:79] offset:16
	global_load_dwordx4 v[72:75], v5, s[78:79] offset:32
	global_load_dwordx4 v[76:79], v5, s[78:79] offset:48
	s_lshl_b32 s11, s12, 2
	s_add_u32 s11, s11, 0x1100000
	v_mov_b32_e32 v6, s11
	global_load_dword v80, v6, s[4:5]
	global_load_dword v252, v6, s[4:5]
	global_load_dword v252, v6, s[4:5]
	s_add_u32 s12, s8, s20
	s_min_u32 s12, s12, s13
	s_lshl_b32 s11, s12, 12
	v_add_u32_e32 v5, s11, v1
	global_load_dwordx4 v[88:91], v5, s[78:79] offset:0
	global_load_dwordx4 v[92:95], v5, s[78:79] offset:16
	global_load_dwordx4 v[96:99], v5, s[78:79] offset:32
	global_load_dwordx4 v[100:103], v5, s[78:79] offset:48
	s_lshl_b32 s11, s12, 2
	s_add_u32 s11, s11, 0x1100000
	v_mov_b32_e32 v6, s11
	global_load_dword v104, v6, s[4:5]
	global_load_dword v252, v6, s[4:5]
	global_load_dword v252, v6, s[4:5]
	s_add_u32 s12, s8, s21
	s_min_u32 s12, s12, s13
	s_lshl_b32 s11, s12, 12
	v_add_u32_e32 v5, s11, v1
	global_load_dwordx4 v[136:139], v5, s[78:79] offset:0
	global_load_dwordx4 v[140:143], v5, s[78:79] offset:16
	global_load_dwordx4 v[144:147], v5, s[78:79] offset:32
	global_load_dwordx4 v[148:151], v5, s[78:79] offset:48
	s_lshl_b32 s11, s12, 2
	s_add_u32 s11, s11, 0x1100000
	v_mov_b32_e32 v6, s11
	global_load_dword v152, v6, s[4:5]
	global_load_dword v252, v6, s[4:5]
	global_load_dword v252, v6, s[4:5]
.Lp5h_loop:
	s_add_u32 s12, s8, s22
	s_min_u32 s12, s12, s13
	s_lshl_b32 s11, s12, 12
	v_add_u32_e32 v5, s11, v1
	global_load_dwordx4 v[160:163], v5, s[78:79] offset:0
	global_load_dwordx4 v[164:167], v5, s[78:79] offset:16
	global_load_dwordx4 v[168:171], v5, s[78:79] offset:32
	global_load_dwordx4 v[172:175], v5, s[78:79] offset:48
	s_lshl_b32 s11, s12, 2
	s_add_u32 s11, s11, 0x1100000
	v_mov_b32_e32 v6, s11
	global_load_dword v176, v6, s[4:5]
	s_waitcnt vmcnt(21)
	s_mov_b32 s14, s8
	s_cmp_lt_u32 s14, 0x4200
	s_cbranch_scc0 .Lp5h_done
	v_fmamk_f32 v8, v80, 0x3a800000, v105
	v_mul_f32_e32 v9, 0x4b800000, v8
	v_cmp_gt_f32_e64 s[0:1], s39, v8
	s_nop 1
	v_cndmask_b32_e64 v8, v8, v9, s[0:1]
	v_rsq_f32_e32 v8, v8
	s_nop 0
	v_mul_f32_e32 v9, 0x45800000, v8
	v_cndmask_b32_e64 v8, v8, v9, s[0:1]
	v_pk_mul_f32 v[16:17], v[64:65], v[8:9] op_sel_hi:[1,0]
	v_pk_mul_f32 v[18:19], v[66:67], v[8:9] op_sel_hi:[1,0]
	v_pk_mul_f32 v[20:21], v[68:69], v[8:9] op_sel_hi:[1,0]
	v_pk_mul_f32 v[22:23], v[70:71], v[8:9] op_sel_hi:[1,0]
	v_pk_mul_f32 v[24:25], v[72:73], v[8:9] op_sel_hi:[1,0]
	v_pk_mul_f32 v[26:27], v[74:75], v[8:9] op_sel_hi:[1,0]
	v_pk_mul_f32 v[28:29], v[76:77], v[8:9] op_sel_hi:[1,0]
	v_pk_mul_f32 v[30:31], v[78:79], v[8:9] op_sel_hi:[1,0]
	v_pk_mul_f32 v[16:17], v[16:17], v[112:113]
	v_pk_mul_f32 v[18:19], v[18:19], v[114:115]
	v_pk_mul_f32 v[20:21], v[20:21], v[116:117]
	v_pk_mul_f32 v[22:23], v[22:23], v[118:119]
	v_pk_mul_f32 v[24:25], v[24:25], v[120:121]
	v_pk_mul_f32 v[26:27], v[26:27], v[122:123]
	v_pk_mul_f32 v[28:29], v[28:29], v[124:125]
	v_pk_mul_f32 v[30:31], v[30:31], v[126:127]
	v_cvt_pk_bf16_f32 v40, v16, v17
	v_cvt_pk_bf16_f32 v41, v18, v19
	v_cvt_pk_bf16_f32 v42, v20, v21
	v_cvt_pk_bf16_f32 v43, v22, v23
	v_cvt_pk_bf16_f32 v44, v24, v25
	v_cvt_pk_bf16_f32 v45, v26, v27
	v_cvt_pk_bf16_f32 v46, v28, v29
	v_cvt_pk_bf16_f32 v47, v30, v31
	s_lshl_b32 s11, s14, 11
	v_add_u32_e32 v7, s11, v2
	global_store_dwordx4 v7, v[40:43], s[2:3]
	global_store_dwordx4 v7, v[44:47], s[2:3] offset:16
	s_add_u32 s12, s8, s23
	s_min_u32 s12, s12, s13
	s_lshl_b32 s11, s12, 12
	v_add_u32_e32 v5, s11, v1
	global_load_dwordx4 v[64:67], v5, s[78:79] offset:0
	global_load_dwordx4 v[68:71], v5, s[78:79] offset:16
	global_load_dwordx4 v[72:75], v5, s[78:79] offset:32
	global_load_dwordx4 v[76:79], v5, s[78:79] offset:48
	s_lshl_b32 s11, s12, 2
	s_add_u32 s11, s11, 0x1100000
	v_mov_b32_e32 v6, s11
	global_load_dword v80, v6, s[4:5]
	s_waitcnt vmcnt(21)
	s_add_u32 s14, s8, s20
	s_cmp_lt_u32 s14, 0x4200
	s_cbranch_scc0 .Lp5h_done
; __device__ __forceinline__ float bflo(unsigned u) { return __uint_as_float(u << 16); }
; __device__ __forceinline__ float bfhi(unsigned u) { return __uint_as_float(u & 0xffff0000u); }
; __device__ __forceinline__ void phase5(const Params& p, char* smem, const bool store_x = true) {
;     ...
;     const uint4 cur_ha = pf_ha, cur_hb = pf_hb; const float cur_rs = rsqrtf(pf_ss * (1.f / 1024.f) + EPSF);
;     ...
;     float2v h2[8];
;     {
;       const uint4 a = cur_ha;
;       const uint4 b2 = cur_hb;
;       h2[0] = float2v{bflo(a.x), bfhi(a.x)}; h2[1] = float2v{bflo(a.y), bfhi(a.y)}; h2[2] = float2v{bflo(a.z), bfhi(a.z)}; h2[3] = float2v{bflo(a.w), bfhi(a.w)};
;       h2[4] = float2v{bflo(b2.x), bfhi(b2.x)}; h2[5] = float2v{bflo(b2.y), bfhi(b2.y)}; h2[6] = float2v{bflo(b2.z), bfhi(b2.z)}; h2[7] = float2v{bflo(b2.w), bfhi(b2.w)};
; #pragma unroll
;       for (int i = 0; i < 8; i++) h2[i] = h2[i] * gf[i] * cur_rs;
;     }
	v_fmamk_f32 v8, v104, 0x3a800000, v105
	v_mul_f32_e32 v9, 0x4b800000, v8
	v_cmp_gt_f32_e64 s[0:1], s39, v8
	s_nop 1
	v_cndmask_b32_e64 v8, v8, v9, s[0:1]
	v_rsq_f32_e32 v8, v8
	s_nop 0
	v_mul_f32_e32 v9, 0x45800000, v8
	v_cndmask_b32_e64 v8, v8, v9, s[0:1]
	v_pk_mul_f32 v[16:17], v[88:89], v[8:9] op_sel_hi:[1,0]
	v_pk_mul_f32 v[18:19], v[90:91], v[8:9] op_sel_hi:[1,0]
	v_pk_mul_f32 v[20:21], v[92:93], v[8:9] op_sel_hi:[1,0]
	v_pk_mul_f32 v[22:23], v[94:95], v[8:9] op_sel_hi:[1,0]
	v_pk_mul_f32 v[24:25], v[96:97], v[8:9] op_sel_hi:[1,0]
	v_pk_mul_f32 v[26:27], v[98:99], v[8:9] op_sel_hi:[1,0]
	v_pk_mul_f32 v[28:29], v[100:101], v[8:9] op_sel_hi:[1,0]
	v_pk_mul_f32 v[30:31], v[102:103], v[8:9] op_sel_hi:[1,0]
	v_pk_mul_f32 v[16:17], v[16:17], v[112:113]
	v_pk_mul_f32 v[18:19], v[18:19], v[114:115]
	v_pk_mul_f32 v[20:21], v[20:21], v[116:117]
	v_pk_mul_f32 v[22:23], v[22:23], v[118:119]
	v_pk_mul_f32 v[24:25], v[24:25], v[120:121]
	v_pk_mul_f32 v[26:27], v[26:27], v[122:123]
	v_pk_mul_f32 v[28:29], v[28:29], v[124:125]
	v_pk_mul_f32 v[30:31], v[30:31], v[126:127]
	v_cvt_pk_bf16_f32 v40, v16, v17
	v_cvt_pk_bf16_f32 v41, v18, v19
	v_cvt_pk_bf16_f32 v42, v20, v21
	v_cvt_pk_bf16_f32 v43, v22, v23
	v_cvt_pk_bf16_f32 v44, v24, v25
	v_cvt_pk_bf16_f32 v45, v26, v27
	v_cvt_pk_bf16_f32 v46, v28, v29
	v_cvt_pk_bf16_f32 v47, v30, v31
	s_lshl_b32 s11, s14, 11
	v_add_u32_e32 v7, s11, v2
	global_store_dwordx4 v7, v[40:43], s[2:3]
	global_store_dwordx4 v7, v[44:47], s[2:3] offset:16
	s_add_u32 s12, s8, s24
	s_min_u32 s12, s12, s13
	s_lshl_b32 s11, s12, 12
	v_add_u32_e32 v5, s11, v1
	global_load_dwordx4 v[88:91], v5, s[78:79] offset:0
	global_load_dwordx4 v[92:95], v5, s[78:79] offset:16
	global_load_dwordx4 v[96:99], v5, s[78:79] offset:32
	global_load_dwordx4 v[100:103], v5, s[78:79] offset:48
	s_lshl_b32 s11, s12, 2
	s_add_u32 s11, s11, 0x1100000
	v_mov_b32_e32 v6, s11
	global_load_dword v104, v6, s[4:5]
	s_waitcnt vmcnt(21)
	s_add_u32 s14, s8, s21
	s_cmp_lt_u32 s14, 0x4200
	s_cbranch_scc0 .Lp5h_done
	v_fmamk_f32 v8, v152, 0x3a800000, v105
	v_mul_f32_e32 v9, 0x4b800000, v8
	v_cmp_gt_f32_e64 s[0:1], s39, v8
	s_nop 1
	v_cndmask_b32_e64 v8, v8, v9, s[0:1]
	v_rsq_f32_e32 v8, v8
	s_nop 0
	v_mul_f32_e32 v9, 0x45800000, v8
	v_cndmask_b32_e64 v8, v8, v9, s[0:1]
	v_pk_mul_f32 v[16:17], v[136:137], v[8:9] op_sel_hi:[1,0]
	v_pk_mul_f32 v[18:19], v[138:139], v[8:9] op_sel_hi:[1,0]
	v_pk_mul_f32 v[20:21], v[140:141], v[8:9] op_sel_hi:[1,0]
	v_pk_mul_f32 v[22:23], v[142:143], v[8:9] op_sel_hi:[1,0]
	v_pk_mul_f32 v[24:25], v[144:145], v[8:9] op_sel_hi:[1,0]
	v_pk_mul_f32 v[26:27], v[146:147], v[8:9] op_sel_hi:[1,0]
	v_pk_mul_f32 v[28:29], v[148:149], v[8:9] op_sel_hi:[1,0]
	v_pk_mul_f32 v[30:31], v[150:151], v[8:9] op_sel_hi:[1,0]
	v_pk_mul_f32 v[16:17], v[16:17], v[112:113]
	v_pk_mul_f32 v[18:19], v[18:19], v[114:115]
	v_pk_mul_f32 v[20:21], v[20:21], v[116:117]
	v_pk_mul_f32 v[22:23], v[22:23], v[118:119]
	v_pk_mul_f32 v[24:25], v[24:25], v[120:121]
	v_pk_mul_f32 v[26:27], v[26:27], v[122:123]
	v_pk_mul_f32 v[28:29], v[28:29], v[124:125]
	v_pk_mul_f32 v[30:31], v[30:31], v[126:127]
	v_cvt_pk_bf16_f32 v40, v16, v17
	v_cvt_pk_bf16_f32 v41, v18, v19
	v_cvt_pk_bf16_f32 v42, v20, v21
	v_cvt_pk_bf16_f32 v43, v22, v23
	v_cvt_pk_bf16_f32 v44, v24, v25
	v_cvt_pk_bf16_f32 v45, v26, v27
	v_cvt_pk_bf16_f32 v46, v28, v29
	v_cvt_pk_bf16_f32 v47, v30, v31
	s_lshl_b32 s11, s14, 11
	v_add_u32_e32 v7, s11, v2
	global_store_dwordx4 v7, v[40:43], s[2:3]
	global_store_dwordx4 v7, v[44:47], s[2:3] offset:16
	s_add_u32 s12, s8, s25
	s_min_u32 s12, s12, s13
	s_lshl_b32 s11, s12, 12
	v_add_u32_e32 v5, s11, v1
	global_load_dwordx4 v[136:139], v5, s[78:79] offset:0
	global_load_dwordx4 v[140:143], v5, s[78:79] offset:16
	global_load_dwordx4 v[144:147], v5, s[78:79] offset:32
	global_load_dwordx4 v[148:151], v5, s[78:79] offset:48
	s_lshl_b32 s11, s12, 2
	s_add_u32 s11, s11, 0x1100000
	v_mov_b32_e32 v6, s11
	global_load_dword v152, v6, s[4:5]
	s_waitcnt vmcnt(21)
	s_add_u32 s14, s8, s22
	s_cmp_lt_u32 s14, 0x4200
	s_cbranch_scc0 .Lp5h_done
	v_fmamk_f32 v8, v176, 0x3a800000, v105
	v_mul_f32_e32 v9, 0x4b800000, v8
	v_cmp_gt_f32_e64 s[0:1], s39, v8
	s_nop 1
	v_cndmask_b32_e64 v8, v8, v9, s[0:1]
	v_rsq_f32_e32 v8, v8
	s_nop 0
	v_mul_f32_e32 v9, 0x45800000, v8
	v_cndmask_b32_e64 v8, v8, v9, s[0:1]
	v_pk_mul_f32 v[16:17], v[160:161], v[8:9] op_sel_hi:[1,0]
	v_pk_mul_f32 v[18:19], v[162:163], v[8:9] op_sel_hi:[1,0]
	v_pk_mul_f32 v[20:21], v[164:165], v[8:9] op_sel_hi:[1,0]
	v_pk_mul_f32 v[22:23], v[166:167], v[8:9] op_sel_hi:[1,0]
	v_pk_mul_f32 v[24:25], v[168:169], v[8:9] op_sel_hi:[1,0]
	v_pk_mul_f32 v[26:27], v[170:171], v[8:9] op_sel_hi:[1,0]
	v_pk_mul_f32 v[28:29], v[172:173], v[8:9] op_sel_hi:[1,0]
	v_pk_mul_f32 v[30:31], v[174:175], v[8:9] op_sel_hi:[1,0]
	v_pk_mul_f32 v[16:17], v[16:17], v[112:113]
	v_pk_mul_f32 v[18:19], v[18:19], v[114:115]
	v_pk_mul_f32 v[20:21], v[20:21], v[116:117]
	v_pk_mul_f32 v[22:23], v[22:23], v[118:119]
	v_pk_mul_f32 v[24:25], v[24:25], v[120:121]
	v_pk_mul_f32 v[26:27], v[26:27], v[122:123]
	v_pk_mul_f32 v[28:29], v[28:29], v[124:125]
	v_pk_mul_f32 v[30:31], v[30:31], v[126:127]
	v_cvt_pk_bf16_f32 v40, v16, v17
	v_cvt_pk_bf16_f32 v41, v18, v19
	v_cvt_pk_bf16_f32 v42, v20, v21
	v_cvt_pk_bf16_f32 v43, v22, v23
	v_cvt_pk_bf16_f32 v44, v24, v25
	v_cvt_pk_bf16_f32 v45, v26, v27
	v_cvt_pk_bf16_f32 v46, v28, v29
	v_cvt_pk_bf16_f32 v47, v30, v31
	s_lshl_b32 s11, s14, 11
	v_add_u32_e32 v7, s11, v2
	global_store_dwordx4 v7, v[40:43], s[2:3]
	global_store_dwordx4 v7, v[44:47], s[2:3] offset:16
	s_add_u32 s8, s8, s23
	s_branch .Lp5h_loop
.Lp5h_done:
	s_waitcnt vmcnt(0)
.LBB0_1522:
	v_accvgpr_read_b32 v234, a124
	v_accvgpr_read_b32 v237, a125
	v_accvgpr_read_b32 v240, a130
